# phase-0 pool-weight fold loop hand-scheduled: uniform pool_w/pool_scale operands staged once per wave in LDS (broadcast ds_read_b128) instead of 160 uniform VMEM loads, W_out rows streamed 48 deep wit
# speedup vs baseline: 1.0088x; 1.0088x over previous
.LBB0_67:
	v_ashrrev_i32_e32 v6, 15, v0
	v_lshlrev_b32_e32 v8, 7, v6
	v_ashrrev_i32_e32 v58, 8, v0
	v_ashrrev_i32_e32 v7, 31, v6
	v_ashrrev_i32_e32 v9, 31, v8
	v_and_b32_e32 v10, 0x3ff, v1
	v_lshlrev_b64 v[4:5], 16, v[6:7]
	v_lshlrev_b32_e32 v2, 9, v58
	v_lshl_add_u64 v[6:7], v[8:9], 2, s[14:15]
	v_lshlrev_b64 v[8:9], 12, v[8:9]
	v_lshl_add_u64 v[4:5], s[12:13], 0, v[4:5]
	v_and_b32_e32 v2, 0xf800, v2
	v_lshl_or_b32 v8, v10, 2, v8
	v_mov_b32_e32 v10, 0
	v_lshl_add_u64 v[4:5], v[4:5], 0, v[2:3]
	v_lshl_add_u64 v[8:9], s[10:11], 0, v[8:9]
	s_mov_b64 s[22:23], 0
	v_mov_b32_e32 v11, v10
	v_mov_b32_e32 v12, v10
	v_mov_b32_e32 v13, v10
	v_mbcnt_lo_u32_b32 v61, -1, 0
	v_mbcnt_hi_u32_b32 v61, -1, v61
	v_lshlrev_b32_e32 v61, 2, v61
	s_lshl_b32 s24, s94, 14
	v_add_u32_e32 v62, s24, v61
	v_mov_b32_e32 v63, s24
	v_readfirstlane_b32 s0, v4
	v_readfirstlane_b32 s1, v5
	v_readfirstlane_b32 s22, v6
	v_readfirstlane_b32 s23, v7
	s_nop 4
	global_load_dword v14, v61, s[0:1]
	global_load_dword v15, v61, s[0:1] offset:256
	global_load_dword v16, v61, s[0:1] offset:512
	global_load_dword v17, v61, s[0:1] offset:768
	global_load_dword v18, v61, s[0:1] offset:1024
	global_load_dword v19, v61, s[0:1] offset:1280
	global_load_dword v20, v61, s[0:1] offset:1536
	global_load_dword v21, v61, s[0:1] offset:1792
	global_load_dword v22, v61, s[22:23]
	global_load_dword v23, v61, s[22:23] offset:256
	v_readfirstlane_b32 s0, v8
	v_readfirstlane_b32 s1, v9
	s_nop 1
	v_subrev_u32_e32 v60, s0, v8
	s_add_u32 s0, s0, 0xfffe1000
	s_addc_u32 s1, s1, -1
	global_load_dword v64, v60, s[0:1]
	s_add_u32 s0, s0, 0x1000
	s_addc_u32 s1, s1, 0
	global_load_dword v65, v60, s[0:1]
	s_add_u32 s0, s0, 0x1000
	s_addc_u32 s1, s1, 0
	global_load_dword v66, v60, s[0:1]
	s_add_u32 s0, s0, 0x1000
	s_addc_u32 s1, s1, 0
	global_load_dword v67, v60, s[0:1]
	s_add_u32 s0, s0, 0x1000
	s_addc_u32 s1, s1, 0
	global_load_dword v68, v60, s[0:1]
	s_add_u32 s0, s0, 0x1000
	s_addc_u32 s1, s1, 0
	global_load_dword v69, v60, s[0:1]
	s_add_u32 s0, s0, 0x1000
	s_addc_u32 s1, s1, 0
	global_load_dword v70, v60, s[0:1]
	s_add_u32 s0, s0, 0x1000
	s_addc_u32 s1, s1, 0
	global_load_dword v71, v60, s[0:1]
	s_add_u32 s0, s0, 0x1000
	s_addc_u32 s1, s1, 0
	global_load_dword v72, v60, s[0:1]
	s_add_u32 s0, s0, 0x1000
	s_addc_u32 s1, s1, 0
	global_load_dword v73, v60, s[0:1]
	s_add_u32 s0, s0, 0x1000
	s_addc_u32 s1, s1, 0
	global_load_dword v74, v60, s[0:1]
	s_add_u32 s0, s0, 0x1000
	s_addc_u32 s1, s1, 0
	global_load_dword v75, v60, s[0:1]
	s_add_u32 s0, s0, 0x1000
	s_addc_u32 s1, s1, 0
	global_load_dword v76, v60, s[0:1]
	s_add_u32 s0, s0, 0x1000
	s_addc_u32 s1, s1, 0
	global_load_dword v77, v60, s[0:1]
	s_add_u32 s0, s0, 0x1000
	s_addc_u32 s1, s1, 0
	global_load_dword v78, v60, s[0:1]
	s_add_u32 s0, s0, 0x1000
	s_addc_u32 s1, s1, 0
	global_load_dword v79, v60, s[0:1]
	s_add_u32 s0, s0, 0x1000
	s_addc_u32 s1, s1, 0
	global_load_dword v80, v60, s[0:1]
	s_add_u32 s0, s0, 0x1000
	s_addc_u32 s1, s1, 0
	global_load_dword v81, v60, s[0:1]
	s_add_u32 s0, s0, 0x1000
	s_addc_u32 s1, s1, 0
	global_load_dword v82, v60, s[0:1]
	s_add_u32 s0, s0, 0x1000
	s_addc_u32 s1, s1, 0
	global_load_dword v83, v60, s[0:1]
	s_add_u32 s0, s0, 0x1000
	s_addc_u32 s1, s1, 0
	global_load_dword v84, v60, s[0:1]
	s_add_u32 s0, s0, 0x1000
	s_addc_u32 s1, s1, 0
	global_load_dword v85, v60, s[0:1]
	s_add_u32 s0, s0, 0x1000
	s_addc_u32 s1, s1, 0
	global_load_dword v86, v60, s[0:1]
	s_add_u32 s0, s0, 0x1000
	s_addc_u32 s1, s1, 0
	global_load_dword v87, v60, s[0:1]
	s_add_u32 s0, s0, 0x1000
	s_addc_u32 s1, s1, 0
	global_load_dword v88, v60, s[0:1]
	s_add_u32 s0, s0, 0x1000
	s_addc_u32 s1, s1, 0
	global_load_dword v89, v60, s[0:1]
	s_add_u32 s0, s0, 0x1000
	s_addc_u32 s1, s1, 0
	global_load_dword v90, v60, s[0:1]
	s_add_u32 s0, s0, 0x1000
	s_addc_u32 s1, s1, 0
	global_load_dword v91, v60, s[0:1]
	s_add_u32 s0, s0, 0x1000
	s_addc_u32 s1, s1, 0
	global_load_dword v92, v60, s[0:1]
	s_add_u32 s0, s0, 0x1000
	s_addc_u32 s1, s1, 0
	global_load_dword v93, v60, s[0:1]
	s_add_u32 s0, s0, 0x1000
	s_addc_u32 s1, s1, 0
	global_load_dword v94, v60, s[0:1]
	s_add_u32 s0, s0, 0x1000
	s_addc_u32 s1, s1, 0
	global_load_dword v95, v60, s[0:1]
	s_add_u32 s0, s0, 0x1000
	s_addc_u32 s1, s1, 0
	global_load_dword v96, v60, s[0:1]
	s_add_u32 s0, s0, 0x1000
	s_addc_u32 s1, s1, 0
	global_load_dword v97, v60, s[0:1]
	s_add_u32 s0, s0, 0x1000
	s_addc_u32 s1, s1, 0
	global_load_dword v98, v60, s[0:1]
	s_add_u32 s0, s0, 0x1000
	s_addc_u32 s1, s1, 0
	global_load_dword v99, v60, s[0:1]
	s_add_u32 s0, s0, 0x1000
	s_addc_u32 s1, s1, 0
	global_load_dword v100, v60, s[0:1]
	s_add_u32 s0, s0, 0x1000
	s_addc_u32 s1, s1, 0
	global_load_dword v101, v60, s[0:1]
	s_add_u32 s0, s0, 0x1000
	s_addc_u32 s1, s1, 0
	global_load_dword v102, v60, s[0:1]
	s_add_u32 s0, s0, 0x1000
	s_addc_u32 s1, s1, 0
	global_load_dword v103, v60, s[0:1]
	s_add_u32 s0, s0, 0x1000
	s_addc_u32 s1, s1, 0
	global_load_dword v104, v60, s[0:1]
	s_add_u32 s0, s0, 0x1000
	s_addc_u32 s1, s1, 0
	global_load_dword v105, v60, s[0:1]
	s_add_u32 s0, s0, 0x1000
	s_addc_u32 s1, s1, 0
	global_load_dword v106, v60, s[0:1]
	s_add_u32 s0, s0, 0x1000
	s_addc_u32 s1, s1, 0
	global_load_dword v107, v60, s[0:1]
	s_add_u32 s0, s0, 0x1000
	s_addc_u32 s1, s1, 0
	global_load_dword v108, v60, s[0:1]
	s_add_u32 s0, s0, 0x1000
	s_addc_u32 s1, s1, 0
	global_load_dword v109, v60, s[0:1]
	s_add_u32 s0, s0, 0x1000
	s_addc_u32 s1, s1, 0
	global_load_dword v110, v60, s[0:1]
	s_add_u32 s0, s0, 0x1000
	s_addc_u32 s1, s1, 0
	global_load_dword v111, v60, s[0:1]
	s_add_u32 s0, s0, 0x1000
	s_addc_u32 s1, s1, 0
	s_waitcnt vmcnt(48)
	ds_write_b32 v62, v14
	ds_write_b32 v62, v15 offset:256
	ds_write_b32 v62, v16 offset:512
	ds_write_b32 v62, v17 offset:768
	ds_write_b32 v62, v18 offset:1024
	ds_write_b32 v62, v19 offset:1280
	ds_write_b32 v62, v20 offset:1536
	ds_write_b32 v62, v21 offset:1792
	ds_write_b32 v62, v22 offset:2048
	ds_write_b32 v62, v23 offset:2304
	s_waitcnt lgkmcnt(0)
	ds_read_b128 v[128:131], v63 offset:2048
	ds_read_b128 v[132:135], v63 offset:2064
	ds_read_b128 v[136:139], v63 offset:2080
	ds_read_b128 v[140:143], v63 offset:2096
	ds_read_b128 v[144:147], v63
	ds_read_b128 v[148:151], v63 offset:16
	ds_read_b128 v[152:155], v63 offset:32
	ds_read_b128 v[156:159], v63 offset:48
	ds_read_b128 v[170:173], v63 offset:512
	ds_read_b128 v[174:177], v63 offset:528
	ds_read_b128 v[178:181], v63 offset:544
	ds_read_b128 v[182:185], v63 offset:560
	ds_read_b128 v[186:189], v63 offset:1024
	ds_read_b128 v[190:193], v63 offset:1040
	ds_read_b128 v[194:197], v63 offset:1056
	ds_read_b128 v[198:201], v63 offset:1072
	ds_read_b128 v[202:205], v63 offset:1536
	ds_read_b128 v[206:209], v63 offset:1552
	ds_read_b128 v[210:213], v63 offset:1568
	ds_read_b128 v[214:217], v63 offset:1584
	s_waitcnt vmcnt(32)
	global_load_dword v112, v60, s[0:1]
	s_add_u32 s0, s0, 0x1000
	s_addc_u32 s1, s1, 0
	global_load_dword v113, v60, s[0:1]
	s_add_u32 s0, s0, 0x1000
	s_addc_u32 s1, s1, 0
	global_load_dword v114, v60, s[0:1]
	s_add_u32 s0, s0, 0x1000
	s_addc_u32 s1, s1, 0
	global_load_dword v115, v60, s[0:1]
	s_add_u32 s0, s0, 0x1000
	s_addc_u32 s1, s1, 0
	global_load_dword v116, v60, s[0:1]
	s_add_u32 s0, s0, 0x1000
	s_addc_u32 s1, s1, 0
	global_load_dword v117, v60, s[0:1]
	s_add_u32 s0, s0, 0x1000
	s_addc_u32 s1, s1, 0
	global_load_dword v118, v60, s[0:1]
	s_add_u32 s0, s0, 0x1000
	s_addc_u32 s1, s1, 0
	global_load_dword v119, v60, s[0:1]
	s_add_u32 s0, s0, 0x1000
	s_addc_u32 s1, s1, 0
	global_load_dword v120, v60, s[0:1]
	s_add_u32 s0, s0, 0x1000
	s_addc_u32 s1, s1, 0
	global_load_dword v121, v60, s[0:1]
	s_add_u32 s0, s0, 0x1000
	s_addc_u32 s1, s1, 0
	global_load_dword v122, v60, s[0:1]
	s_add_u32 s0, s0, 0x1000
	s_addc_u32 s1, s1, 0
	global_load_dword v123, v60, s[0:1]
	s_add_u32 s0, s0, 0x1000
	s_addc_u32 s1, s1, 0
	global_load_dword v124, v60, s[0:1]
	s_add_u32 s0, s0, 0x1000
	s_addc_u32 s1, s1, 0
	global_load_dword v125, v60, s[0:1]
	s_add_u32 s0, s0, 0x1000
	s_addc_u32 s1, s1, 0
	global_load_dword v126, v60, s[0:1]
	s_add_u32 s0, s0, 0x1000
	s_addc_u32 s1, s1, 0
	global_load_dword v127, v60, s[0:1]
	s_add_u32 s0, s0, 0x1000
	s_addc_u32 s1, s1, 0
	s_waitcnt lgkmcnt(0)
	v_mul_f32_e32 v59, v128, v64
	v_fmac_f32_e32 v10, v144, v59
	v_fmac_f32_e32 v11, v170, v59
	v_fmac_f32_e32 v12, v186, v59
	v_fmac_f32_e32 v13, v202, v59
	v_mul_f32_e32 v59, v129, v65
	v_fmac_f32_e32 v10, v145, v59
	v_fmac_f32_e32 v11, v171, v59
	v_fmac_f32_e32 v12, v187, v59
	v_fmac_f32_e32 v13, v203, v59
	v_mul_f32_e32 v59, v130, v66
	v_fmac_f32_e32 v10, v146, v59
	v_fmac_f32_e32 v11, v172, v59
	v_fmac_f32_e32 v12, v188, v59
	v_fmac_f32_e32 v13, v204, v59
	v_mul_f32_e32 v59, v131, v67
	v_fmac_f32_e32 v10, v147, v59
	v_fmac_f32_e32 v11, v173, v59
	v_fmac_f32_e32 v12, v189, v59
	v_fmac_f32_e32 v13, v205, v59
	v_mul_f32_e32 v59, v132, v68
	v_fmac_f32_e32 v10, v148, v59
	v_fmac_f32_e32 v11, v174, v59
	v_fmac_f32_e32 v12, v190, v59
	v_fmac_f32_e32 v13, v206, v59
	v_mul_f32_e32 v59, v133, v69
	v_fmac_f32_e32 v10, v149, v59
	v_fmac_f32_e32 v11, v175, v59
	v_fmac_f32_e32 v12, v191, v59
	v_fmac_f32_e32 v13, v207, v59
	v_mul_f32_e32 v59, v134, v70
	v_fmac_f32_e32 v10, v150, v59
	v_fmac_f32_e32 v11, v176, v59
	v_fmac_f32_e32 v12, v192, v59
	v_fmac_f32_e32 v13, v208, v59
	v_mul_f32_e32 v59, v135, v71
	v_fmac_f32_e32 v10, v151, v59
	v_fmac_f32_e32 v11, v177, v59
	v_fmac_f32_e32 v12, v193, v59
	v_fmac_f32_e32 v13, v209, v59
	v_mul_f32_e32 v59, v136, v72
	v_fmac_f32_e32 v10, v152, v59
	v_fmac_f32_e32 v11, v178, v59
	v_fmac_f32_e32 v12, v194, v59
	v_fmac_f32_e32 v13, v210, v59
	v_mul_f32_e32 v59, v137, v73
	v_fmac_f32_e32 v10, v153, v59
	v_fmac_f32_e32 v11, v179, v59
	v_fmac_f32_e32 v12, v195, v59
	v_fmac_f32_e32 v13, v211, v59
	v_mul_f32_e32 v59, v138, v74
	v_fmac_f32_e32 v10, v154, v59
	v_fmac_f32_e32 v11, v180, v59
	v_fmac_f32_e32 v12, v196, v59
	v_fmac_f32_e32 v13, v212, v59
	v_mul_f32_e32 v59, v139, v75
	v_fmac_f32_e32 v10, v155, v59
	v_fmac_f32_e32 v11, v181, v59
	v_fmac_f32_e32 v12, v197, v59
	v_fmac_f32_e32 v13, v213, v59
	v_mul_f32_e32 v59, v140, v76
	v_fmac_f32_e32 v10, v156, v59
	v_fmac_f32_e32 v11, v182, v59
	v_fmac_f32_e32 v12, v198, v59
	v_fmac_f32_e32 v13, v214, v59
	v_mul_f32_e32 v59, v141, v77
	v_fmac_f32_e32 v10, v157, v59
	v_fmac_f32_e32 v11, v183, v59
	v_fmac_f32_e32 v12, v199, v59
	v_fmac_f32_e32 v13, v215, v59
	v_mul_f32_e32 v59, v142, v78
	v_fmac_f32_e32 v10, v158, v59
	v_fmac_f32_e32 v11, v184, v59
	v_fmac_f32_e32 v12, v200, v59
	v_fmac_f32_e32 v13, v216, v59
	v_mul_f32_e32 v59, v143, v79
	v_fmac_f32_e32 v10, v159, v59
	v_fmac_f32_e32 v11, v185, v59
	v_fmac_f32_e32 v12, v201, v59
	v_fmac_f32_e32 v13, v217, v59
	ds_read_b128 v[128:131], v63 offset:2112
	ds_read_b128 v[132:135], v63 offset:2128
	ds_read_b128 v[136:139], v63 offset:2144
	ds_read_b128 v[140:143], v63 offset:2160
	ds_read_b128 v[144:147], v63 offset:64
	ds_read_b128 v[148:151], v63 offset:80
	ds_read_b128 v[152:155], v63 offset:96
	ds_read_b128 v[156:159], v63 offset:112
	ds_read_b128 v[170:173], v63 offset:576
	ds_read_b128 v[174:177], v63 offset:592
	ds_read_b128 v[178:181], v63 offset:608
	ds_read_b128 v[182:185], v63 offset:624
	ds_read_b128 v[186:189], v63 offset:1088
	ds_read_b128 v[190:193], v63 offset:1104
	ds_read_b128 v[194:197], v63 offset:1120
	ds_read_b128 v[198:201], v63 offset:1136
	ds_read_b128 v[202:205], v63 offset:1600
	ds_read_b128 v[206:209], v63 offset:1616
	ds_read_b128 v[210:213], v63 offset:1632
	ds_read_b128 v[214:217], v63 offset:1648
	s_waitcnt vmcnt(32)
	global_load_dword v64, v60, s[0:1]
	s_add_u32 s0, s0, 0x1000
	s_addc_u32 s1, s1, 0
	global_load_dword v65, v60, s[0:1]
	s_add_u32 s0, s0, 0x1000
	s_addc_u32 s1, s1, 0
	global_load_dword v66, v60, s[0:1]
	s_add_u32 s0, s0, 0x1000
	s_addc_u32 s1, s1, 0
	global_load_dword v67, v60, s[0:1]
	s_add_u32 s0, s0, 0x1000
	s_addc_u32 s1, s1, 0
	global_load_dword v68, v60, s[0:1]
	s_add_u32 s0, s0, 0x1000
	s_addc_u32 s1, s1, 0
	global_load_dword v69, v60, s[0:1]
	s_add_u32 s0, s0, 0x1000
	s_addc_u32 s1, s1, 0
	global_load_dword v70, v60, s[0:1]
	s_add_u32 s0, s0, 0x1000
	s_addc_u32 s1, s1, 0
	global_load_dword v71, v60, s[0:1]
	s_add_u32 s0, s0, 0x1000
	s_addc_u32 s1, s1, 0
	global_load_dword v72, v60, s[0:1]
	s_add_u32 s0, s0, 0x1000
	s_addc_u32 s1, s1, 0
	global_load_dword v73, v60, s[0:1]
	s_add_u32 s0, s0, 0x1000
	s_addc_u32 s1, s1, 0
	global_load_dword v74, v60, s[0:1]
	s_add_u32 s0, s0, 0x1000
	s_addc_u32 s1, s1, 0
	global_load_dword v75, v60, s[0:1]
	s_add_u32 s0, s0, 0x1000
	s_addc_u32 s1, s1, 0
	global_load_dword v76, v60, s[0:1]
	s_add_u32 s0, s0, 0x1000
	s_addc_u32 s1, s1, 0
	global_load_dword v77, v60, s[0:1]
	s_add_u32 s0, s0, 0x1000
	s_addc_u32 s1, s1, 0
	global_load_dword v78, v60, s[0:1]
	s_add_u32 s0, s0, 0x1000
	s_addc_u32 s1, s1, 0
	global_load_dword v79, v60, s[0:1]
	s_add_u32 s0, s0, 0x1000
	s_addc_u32 s1, s1, 0
	s_waitcnt lgkmcnt(0)
	v_mul_f32_e32 v59, v128, v80
	v_fmac_f32_e32 v10, v144, v59
	v_fmac_f32_e32 v11, v170, v59
	v_fmac_f32_e32 v12, v186, v59
	v_fmac_f32_e32 v13, v202, v59
	v_mul_f32_e32 v59, v129, v81
	v_fmac_f32_e32 v10, v145, v59
	v_fmac_f32_e32 v11, v171, v59
	v_fmac_f32_e32 v12, v187, v59
	v_fmac_f32_e32 v13, v203, v59
	v_mul_f32_e32 v59, v130, v82
	v_fmac_f32_e32 v10, v146, v59
	v_fmac_f32_e32 v11, v172, v59
	v_fmac_f32_e32 v12, v188, v59
	v_fmac_f32_e32 v13, v204, v59
	v_mul_f32_e32 v59, v131, v83
	v_fmac_f32_e32 v10, v147, v59
	v_fmac_f32_e32 v11, v173, v59
	v_fmac_f32_e32 v12, v189, v59
	v_fmac_f32_e32 v13, v205, v59
	v_mul_f32_e32 v59, v132, v84
	v_fmac_f32_e32 v10, v148, v59
	v_fmac_f32_e32 v11, v174, v59
	v_fmac_f32_e32 v12, v190, v59
	v_fmac_f32_e32 v13, v206, v59
	v_mul_f32_e32 v59, v133, v85
	v_fmac_f32_e32 v10, v149, v59
	v_fmac_f32_e32 v11, v175, v59
	v_fmac_f32_e32 v12, v191, v59
	v_fmac_f32_e32 v13, v207, v59
	v_mul_f32_e32 v59, v134, v86
	v_fmac_f32_e32 v10, v150, v59
	v_fmac_f32_e32 v11, v176, v59
	v_fmac_f32_e32 v12, v192, v59
	v_fmac_f32_e32 v13, v208, v59
	v_mul_f32_e32 v59, v135, v87
	v_fmac_f32_e32 v10, v151, v59
	v_fmac_f32_e32 v11, v177, v59
	v_fmac_f32_e32 v12, v193, v59
	v_fmac_f32_e32 v13, v209, v59
	v_mul_f32_e32 v59, v136, v88
	v_fmac_f32_e32 v10, v152, v59
	v_fmac_f32_e32 v11, v178, v59
	v_fmac_f32_e32 v12, v194, v59
	v_fmac_f32_e32 v13, v210, v59
	v_mul_f32_e32 v59, v137, v89
	v_fmac_f32_e32 v10, v153, v59
	v_fmac_f32_e32 v11, v179, v59
	v_fmac_f32_e32 v12, v195, v59
	v_fmac_f32_e32 v13, v211, v59
	v_mul_f32_e32 v59, v138, v90
	v_fmac_f32_e32 v10, v154, v59
	v_fmac_f32_e32 v11, v180, v59
	v_fmac_f32_e32 v12, v196, v59
	v_fmac_f32_e32 v13, v212, v59
	v_mul_f32_e32 v59, v139, v91
	v_fmac_f32_e32 v10, v155, v59
	v_fmac_f32_e32 v11, v181, v59
	v_fmac_f32_e32 v12, v197, v59
	v_fmac_f32_e32 v13, v213, v59
	v_mul_f32_e32 v59, v140, v92
	v_fmac_f32_e32 v10, v156, v59
	v_fmac_f32_e32 v11, v182, v59
	v_fmac_f32_e32 v12, v198, v59
	v_fmac_f32_e32 v13, v214, v59
	v_mul_f32_e32 v59, v141, v93
	v_fmac_f32_e32 v10, v157, v59
	v_fmac_f32_e32 v11, v183, v59
	v_fmac_f32_e32 v12, v199, v59
	v_fmac_f32_e32 v13, v215, v59
	v_mul_f32_e32 v59, v142, v94
	v_fmac_f32_e32 v10, v158, v59
	v_fmac_f32_e32 v11, v184, v59
	v_fmac_f32_e32 v12, v200, v59
	v_fmac_f32_e32 v13, v216, v59
	v_mul_f32_e32 v59, v143, v95
	v_fmac_f32_e32 v10, v159, v59
	v_fmac_f32_e32 v11, v185, v59
	v_fmac_f32_e32 v12, v201, v59
	v_fmac_f32_e32 v13, v217, v59
	ds_read_b128 v[128:131], v63 offset:2176
	ds_read_b128 v[132:135], v63 offset:2192
	ds_read_b128 v[136:139], v63 offset:2208
	ds_read_b128 v[140:143], v63 offset:2224
	ds_read_b128 v[144:147], v63 offset:128
	ds_read_b128 v[148:151], v63 offset:144
	ds_read_b128 v[152:155], v63 offset:160
	ds_read_b128 v[156:159], v63 offset:176
	ds_read_b128 v[170:173], v63 offset:640
	ds_read_b128 v[174:177], v63 offset:656
	ds_read_b128 v[178:181], v63 offset:672
	ds_read_b128 v[182:185], v63 offset:688
	ds_read_b128 v[186:189], v63 offset:1152
	ds_read_b128 v[190:193], v63 offset:1168
	ds_read_b128 v[194:197], v63 offset:1184
	ds_read_b128 v[198:201], v63 offset:1200
	ds_read_b128 v[202:205], v63 offset:1664
	ds_read_b128 v[206:209], v63 offset:1680
	ds_read_b128 v[210:213], v63 offset:1696
	ds_read_b128 v[214:217], v63 offset:1712
	s_waitcnt vmcnt(32)
	global_load_dword v80, v60, s[0:1]
	s_add_u32 s0, s0, 0x1000
	s_addc_u32 s1, s1, 0
	global_load_dword v81, v60, s[0:1]
	s_add_u32 s0, s0, 0x1000
	s_addc_u32 s1, s1, 0
	global_load_dword v82, v60, s[0:1]
	s_add_u32 s0, s0, 0x1000
	s_addc_u32 s1, s1, 0
	global_load_dword v83, v60, s[0:1]
	s_add_u32 s0, s0, 0x1000
	s_addc_u32 s1, s1, 0
	global_load_dword v84, v60, s[0:1]
	s_add_u32 s0, s0, 0x1000
	s_addc_u32 s1, s1, 0
	global_load_dword v85, v60, s[0:1]
	s_add_u32 s0, s0, 0x1000
	s_addc_u32 s1, s1, 0
	global_load_dword v86, v60, s[0:1]
	s_add_u32 s0, s0, 0x1000
	s_addc_u32 s1, s1, 0
	global_load_dword v87, v60, s[0:1]
	s_add_u32 s0, s0, 0x1000
	s_addc_u32 s1, s1, 0
	global_load_dword v88, v60, s[0:1]
	s_add_u32 s0, s0, 0x1000
	s_addc_u32 s1, s1, 0
	global_load_dword v89, v60, s[0:1]
	s_add_u32 s0, s0, 0x1000
	s_addc_u32 s1, s1, 0
	global_load_dword v90, v60, s[0:1]
	s_add_u32 s0, s0, 0x1000
	s_addc_u32 s1, s1, 0
	global_load_dword v91, v60, s[0:1]
	s_add_u32 s0, s0, 0x1000
	s_addc_u32 s1, s1, 0
	global_load_dword v92, v60, s[0:1]
	s_add_u32 s0, s0, 0x1000
	s_addc_u32 s1, s1, 0
	global_load_dword v93, v60, s[0:1]
	s_add_u32 s0, s0, 0x1000
	s_addc_u32 s1, s1, 0
	global_load_dword v94, v60, s[0:1]
	s_add_u32 s0, s0, 0x1000
	s_addc_u32 s1, s1, 0
	global_load_dword v95, v60, s[0:1]
	s_add_u32 s0, s0, 0x1000
	s_addc_u32 s1, s1, 0
	s_waitcnt lgkmcnt(0)
	v_mul_f32_e32 v59, v128, v96
	v_fmac_f32_e32 v10, v144, v59
	v_fmac_f32_e32 v11, v170, v59
	v_fmac_f32_e32 v12, v186, v59
	v_fmac_f32_e32 v13, v202, v59
	v_mul_f32_e32 v59, v129, v97
	v_fmac_f32_e32 v10, v145, v59
	v_fmac_f32_e32 v11, v171, v59
	v_fmac_f32_e32 v12, v187, v59
	v_fmac_f32_e32 v13, v203, v59
	v_mul_f32_e32 v59, v130, v98
	v_fmac_f32_e32 v10, v146, v59
	v_fmac_f32_e32 v11, v172, v59
	v_fmac_f32_e32 v12, v188, v59
	v_fmac_f32_e32 v13, v204, v59
	v_mul_f32_e32 v59, v131, v99
	v_fmac_f32_e32 v10, v147, v59
	v_fmac_f32_e32 v11, v173, v59
	v_fmac_f32_e32 v12, v189, v59
	v_fmac_f32_e32 v13, v205, v59
	v_mul_f32_e32 v59, v132, v100
	v_fmac_f32_e32 v10, v148, v59
	v_fmac_f32_e32 v11, v174, v59
	v_fmac_f32_e32 v12, v190, v59
	v_fmac_f32_e32 v13, v206, v59
	v_mul_f32_e32 v59, v133, v101
	v_fmac_f32_e32 v10, v149, v59
	v_fmac_f32_e32 v11, v175, v59
	v_fmac_f32_e32 v12, v191, v59
	v_fmac_f32_e32 v13, v207, v59
	v_mul_f32_e32 v59, v134, v102
	v_fmac_f32_e32 v10, v150, v59
	v_fmac_f32_e32 v11, v176, v59
	v_fmac_f32_e32 v12, v192, v59
	v_fmac_f32_e32 v13, v208, v59
	v_mul_f32_e32 v59, v135, v103
	v_fmac_f32_e32 v10, v151, v59
	v_fmac_f32_e32 v11, v177, v59
	v_fmac_f32_e32 v12, v193, v59
	v_fmac_f32_e32 v13, v209, v59
	v_mul_f32_e32 v59, v136, v104
	v_fmac_f32_e32 v10, v152, v59
	v_fmac_f32_e32 v11, v178, v59
	v_fmac_f32_e32 v12, v194, v59
	v_fmac_f32_e32 v13, v210, v59
	v_mul_f32_e32 v59, v137, v105
	v_fmac_f32_e32 v10, v153, v59
	v_fmac_f32_e32 v11, v179, v59
	v_fmac_f32_e32 v12, v195, v59
	v_fmac_f32_e32 v13, v211, v59
	v_mul_f32_e32 v59, v138, v106
	v_fmac_f32_e32 v10, v154, v59
	v_fmac_f32_e32 v11, v180, v59
	v_fmac_f32_e32 v12, v196, v59
	v_fmac_f32_e32 v13, v212, v59
	v_mul_f32_e32 v59, v139, v107
	v_fmac_f32_e32 v10, v155, v59
	v_fmac_f32_e32 v11, v181, v59
	v_fmac_f32_e32 v12, v197, v59
	v_fmac_f32_e32 v13, v213, v59
	v_mul_f32_e32 v59, v140, v108
	v_fmac_f32_e32 v10, v156, v59
	v_fmac_f32_e32 v11, v182, v59
	v_fmac_f32_e32 v12, v198, v59
	v_fmac_f32_e32 v13, v214, v59
	v_mul_f32_e32 v59, v141, v109
	v_fmac_f32_e32 v10, v157, v59
	v_fmac_f32_e32 v11, v183, v59
	v_fmac_f32_e32 v12, v199, v59
	v_fmac_f32_e32 v13, v215, v59
	v_mul_f32_e32 v59, v142, v110
	v_fmac_f32_e32 v10, v158, v59
	v_fmac_f32_e32 v11, v184, v59
	v_fmac_f32_e32 v12, v200, v59
	v_fmac_f32_e32 v13, v216, v59
	v_mul_f32_e32 v59, v143, v111
	v_fmac_f32_e32 v10, v159, v59
	v_fmac_f32_e32 v11, v185, v59
	v_fmac_f32_e32 v12, v201, v59
	v_fmac_f32_e32 v13, v217, v59
	ds_read_b128 v[128:131], v63 offset:2240
	ds_read_b128 v[132:135], v63 offset:2256
	ds_read_b128 v[136:139], v63 offset:2272
	ds_read_b128 v[140:143], v63 offset:2288
	ds_read_b128 v[144:147], v63 offset:192
	ds_read_b128 v[148:151], v63 offset:208
	ds_read_b128 v[152:155], v63 offset:224
	ds_read_b128 v[156:159], v63 offset:240
	ds_read_b128 v[170:173], v63 offset:704
	ds_read_b128 v[174:177], v63 offset:720
	ds_read_b128 v[178:181], v63 offset:736
	ds_read_b128 v[182:185], v63 offset:752
	ds_read_b128 v[186:189], v63 offset:1216
	ds_read_b128 v[190:193], v63 offset:1232
	ds_read_b128 v[194:197], v63 offset:1248
	ds_read_b128 v[198:201], v63 offset:1264
	ds_read_b128 v[202:205], v63 offset:1728
	ds_read_b128 v[206:209], v63 offset:1744
	ds_read_b128 v[210:213], v63 offset:1760
	ds_read_b128 v[214:217], v63 offset:1776
	s_waitcnt vmcnt(32)
	global_load_dword v96, v60, s[0:1]
	s_add_u32 s0, s0, 0x1000
	s_addc_u32 s1, s1, 0
	global_load_dword v97, v60, s[0:1]
	s_add_u32 s0, s0, 0x1000
	s_addc_u32 s1, s1, 0
	global_load_dword v98, v60, s[0:1]
	s_add_u32 s0, s0, 0x1000
	s_addc_u32 s1, s1, 0
	global_load_dword v99, v60, s[0:1]
	s_add_u32 s0, s0, 0x1000
	s_addc_u32 s1, s1, 0
	global_load_dword v100, v60, s[0:1]
	s_add_u32 s0, s0, 0x1000
	s_addc_u32 s1, s1, 0
	global_load_dword v101, v60, s[0:1]
	s_add_u32 s0, s0, 0x1000
	s_addc_u32 s1, s1, 0
	global_load_dword v102, v60, s[0:1]
	s_add_u32 s0, s0, 0x1000
	s_addc_u32 s1, s1, 0
	global_load_dword v103, v60, s[0:1]
	s_add_u32 s0, s0, 0x1000
	s_addc_u32 s1, s1, 0
	global_load_dword v104, v60, s[0:1]
	s_add_u32 s0, s0, 0x1000
	s_addc_u32 s1, s1, 0
	global_load_dword v105, v60, s[0:1]
	s_add_u32 s0, s0, 0x1000
	s_addc_u32 s1, s1, 0
	global_load_dword v106, v60, s[0:1]
	s_add_u32 s0, s0, 0x1000
	s_addc_u32 s1, s1, 0
	global_load_dword v107, v60, s[0:1]
	s_add_u32 s0, s0, 0x1000
	s_addc_u32 s1, s1, 0
	global_load_dword v108, v60, s[0:1]
	s_add_u32 s0, s0, 0x1000
	s_addc_u32 s1, s1, 0
	global_load_dword v109, v60, s[0:1]
	s_add_u32 s0, s0, 0x1000
	s_addc_u32 s1, s1, 0
	global_load_dword v110, v60, s[0:1]
	s_add_u32 s0, s0, 0x1000
	s_addc_u32 s1, s1, 0
	global_load_dword v111, v60, s[0:1]
	s_add_u32 s0, s0, 0x1000
	s_addc_u32 s1, s1, 0
	s_waitcnt lgkmcnt(0)
	v_mul_f32_e32 v59, v128, v112
	v_fmac_f32_e32 v10, v144, v59
	v_fmac_f32_e32 v11, v170, v59
	v_fmac_f32_e32 v12, v186, v59
	v_fmac_f32_e32 v13, v202, v59
	v_mul_f32_e32 v59, v129, v113
	v_fmac_f32_e32 v10, v145, v59
	v_fmac_f32_e32 v11, v171, v59
	v_fmac_f32_e32 v12, v187, v59
	v_fmac_f32_e32 v13, v203, v59
	v_mul_f32_e32 v59, v130, v114
	v_fmac_f32_e32 v10, v146, v59
	v_fmac_f32_e32 v11, v172, v59
	v_fmac_f32_e32 v12, v188, v59
	v_fmac_f32_e32 v13, v204, v59
	v_mul_f32_e32 v59, v131, v115
	v_fmac_f32_e32 v10, v147, v59
	v_fmac_f32_e32 v11, v173, v59
	v_fmac_f32_e32 v12, v189, v59
	v_fmac_f32_e32 v13, v205, v59
	v_mul_f32_e32 v59, v132, v116
	v_fmac_f32_e32 v10, v148, v59
	v_fmac_f32_e32 v11, v174, v59
	v_fmac_f32_e32 v12, v190, v59
	v_fmac_f32_e32 v13, v206, v59
	v_mul_f32_e32 v59, v133, v117
	v_fmac_f32_e32 v10, v149, v59
	v_fmac_f32_e32 v11, v175, v59
	v_fmac_f32_e32 v12, v191, v59
	v_fmac_f32_e32 v13, v207, v59
	v_mul_f32_e32 v59, v134, v118
	v_fmac_f32_e32 v10, v150, v59
	v_fmac_f32_e32 v11, v176, v59
	v_fmac_f32_e32 v12, v192, v59
	v_fmac_f32_e32 v13, v208, v59
	v_mul_f32_e32 v59, v135, v119
	v_fmac_f32_e32 v10, v151, v59
	v_fmac_f32_e32 v11, v177, v59
	v_fmac_f32_e32 v12, v193, v59
	v_fmac_f32_e32 v13, v209, v59
	v_mul_f32_e32 v59, v136, v120
	v_fmac_f32_e32 v10, v152, v59
	v_fmac_f32_e32 v11, v178, v59
	v_fmac_f32_e32 v12, v194, v59
	v_fmac_f32_e32 v13, v210, v59
	v_mul_f32_e32 v59, v137, v121
	v_fmac_f32_e32 v10, v153, v59
	v_fmac_f32_e32 v11, v179, v59
	v_fmac_f32_e32 v12, v195, v59
	v_fmac_f32_e32 v13, v211, v59
	v_mul_f32_e32 v59, v138, v122
	v_fmac_f32_e32 v10, v154, v59
	v_fmac_f32_e32 v11, v180, v59
	v_fmac_f32_e32 v12, v196, v59
	v_fmac_f32_e32 v13, v212, v59
	v_mul_f32_e32 v59, v139, v123
	v_fmac_f32_e32 v10, v155, v59
	v_fmac_f32_e32 v11, v181, v59
	v_fmac_f32_e32 v12, v197, v59
	v_fmac_f32_e32 v13, v213, v59
	v_mul_f32_e32 v59, v140, v124
	v_fmac_f32_e32 v10, v156, v59
	v_fmac_f32_e32 v11, v182, v59
	v_fmac_f32_e32 v12, v198, v59
	v_fmac_f32_e32 v13, v214, v59
	v_mul_f32_e32 v59, v141, v125
	v_fmac_f32_e32 v10, v157, v59
	v_fmac_f32_e32 v11, v183, v59
	v_fmac_f32_e32 v12, v199, v59
	v_fmac_f32_e32 v13, v215, v59
	v_mul_f32_e32 v59, v142, v126
	v_fmac_f32_e32 v10, v158, v59
	v_fmac_f32_e32 v11, v184, v59
	v_fmac_f32_e32 v12, v200, v59
	v_fmac_f32_e32 v13, v216, v59
	v_mul_f32_e32 v59, v143, v127
	v_fmac_f32_e32 v10, v159, v59
	v_fmac_f32_e32 v11, v185, v59
	v_fmac_f32_e32 v12, v201, v59
	v_fmac_f32_e32 v13, v217, v59
	ds_read_b128 v[128:131], v63 offset:2304
	ds_read_b128 v[132:135], v63 offset:2320
	ds_read_b128 v[136:139], v63 offset:2336
	ds_read_b128 v[140:143], v63 offset:2352
	ds_read_b128 v[144:147], v63 offset:256
	ds_read_b128 v[148:151], v63 offset:272
	ds_read_b128 v[152:155], v63 offset:288
	ds_read_b128 v[156:159], v63 offset:304
	ds_read_b128 v[170:173], v63 offset:768
	ds_read_b128 v[174:177], v63 offset:784
	ds_read_b128 v[178:181], v63 offset:800
	ds_read_b128 v[182:185], v63 offset:816
	ds_read_b128 v[186:189], v63 offset:1280
	ds_read_b128 v[190:193], v63 offset:1296
	ds_read_b128 v[194:197], v63 offset:1312
	ds_read_b128 v[198:201], v63 offset:1328
	ds_read_b128 v[202:205], v63 offset:1792
	ds_read_b128 v[206:209], v63 offset:1808
	ds_read_b128 v[210:213], v63 offset:1824
	ds_read_b128 v[214:217], v63 offset:1840
	s_waitcnt vmcnt(32)
	global_load_dword v112, v60, s[0:1]
	s_add_u32 s0, s0, 0x1000
	s_addc_u32 s1, s1, 0
	global_load_dword v113, v60, s[0:1]
	s_add_u32 s0, s0, 0x1000
	s_addc_u32 s1, s1, 0
	global_load_dword v114, v60, s[0:1]
	s_add_u32 s0, s0, 0x1000
	s_addc_u32 s1, s1, 0
	global_load_dword v115, v60, s[0:1]
	s_add_u32 s0, s0, 0x1000
	s_addc_u32 s1, s1, 0
	global_load_dword v116, v60, s[0:1]
	s_add_u32 s0, s0, 0x1000
	s_addc_u32 s1, s1, 0
	global_load_dword v117, v60, s[0:1]
	s_add_u32 s0, s0, 0x1000
	s_addc_u32 s1, s1, 0
	global_load_dword v118, v60, s[0:1]
	s_add_u32 s0, s0, 0x1000
	s_addc_u32 s1, s1, 0
	global_load_dword v119, v60, s[0:1]
	s_add_u32 s0, s0, 0x1000
	s_addc_u32 s1, s1, 0
	global_load_dword v120, v60, s[0:1]
	s_add_u32 s0, s0, 0x1000
	s_addc_u32 s1, s1, 0
	global_load_dword v121, v60, s[0:1]
	s_add_u32 s0, s0, 0x1000
	s_addc_u32 s1, s1, 0
	global_load_dword v122, v60, s[0:1]
	s_add_u32 s0, s0, 0x1000
	s_addc_u32 s1, s1, 0
	global_load_dword v123, v60, s[0:1]
	s_add_u32 s0, s0, 0x1000
	s_addc_u32 s1, s1, 0
	global_load_dword v124, v60, s[0:1]
	s_add_u32 s0, s0, 0x1000
	s_addc_u32 s1, s1, 0
	global_load_dword v125, v60, s[0:1]
	s_add_u32 s0, s0, 0x1000
	s_addc_u32 s1, s1, 0
	global_load_dword v126, v60, s[0:1]
	s_add_u32 s0, s0, 0x1000
	s_addc_u32 s1, s1, 0
	global_load_dword v127, v60, s[0:1]
	s_add_u32 s0, s0, 0x1000
	s_addc_u32 s1, s1, 0
	s_waitcnt lgkmcnt(0)
	v_mul_f32_e32 v59, v128, v64
	v_fmac_f32_e32 v10, v144, v59
	v_fmac_f32_e32 v11, v170, v59
	v_fmac_f32_e32 v12, v186, v59
	v_fmac_f32_e32 v13, v202, v59
	v_mul_f32_e32 v59, v129, v65
	v_fmac_f32_e32 v10, v145, v59
	v_fmac_f32_e32 v11, v171, v59
	v_fmac_f32_e32 v12, v187, v59
	v_fmac_f32_e32 v13, v203, v59
	v_mul_f32_e32 v59, v130, v66
	v_fmac_f32_e32 v10, v146, v59
	v_fmac_f32_e32 v11, v172, v59
	v_fmac_f32_e32 v12, v188, v59
	v_fmac_f32_e32 v13, v204, v59
	v_mul_f32_e32 v59, v131, v67
	v_fmac_f32_e32 v10, v147, v59
	v_fmac_f32_e32 v11, v173, v59
	v_fmac_f32_e32 v12, v189, v59
	v_fmac_f32_e32 v13, v205, v59
	v_mul_f32_e32 v59, v132, v68
	v_fmac_f32_e32 v10, v148, v59
	v_fmac_f32_e32 v11, v174, v59
	v_fmac_f32_e32 v12, v190, v59
	v_fmac_f32_e32 v13, v206, v59
	v_mul_f32_e32 v59, v133, v69
	v_fmac_f32_e32 v10, v149, v59
	v_fmac_f32_e32 v11, v175, v59
	v_fmac_f32_e32 v12, v191, v59
	v_fmac_f32_e32 v13, v207, v59
	v_mul_f32_e32 v59, v134, v70
	v_fmac_f32_e32 v10, v150, v59
	v_fmac_f32_e32 v11, v176, v59
	v_fmac_f32_e32 v12, v192, v59
	v_fmac_f32_e32 v13, v208, v59
	v_mul_f32_e32 v59, v135, v71
	v_fmac_f32_e32 v10, v151, v59
	v_fmac_f32_e32 v11, v177, v59
	v_fmac_f32_e32 v12, v193, v59
	v_fmac_f32_e32 v13, v209, v59
	v_mul_f32_e32 v59, v136, v72
	v_fmac_f32_e32 v10, v152, v59
	v_fmac_f32_e32 v11, v178, v59
	v_fmac_f32_e32 v12, v194, v59
	v_fmac_f32_e32 v13, v210, v59
	v_mul_f32_e32 v59, v137, v73
	v_fmac_f32_e32 v10, v153, v59
	v_fmac_f32_e32 v11, v179, v59
	v_fmac_f32_e32 v12, v195, v59
	v_fmac_f32_e32 v13, v211, v59
	v_mul_f32_e32 v59, v138, v74
	v_fmac_f32_e32 v10, v154, v59
	v_fmac_f32_e32 v11, v180, v59
	v_fmac_f32_e32 v12, v196, v59
	v_fmac_f32_e32 v13, v212, v59
	v_mul_f32_e32 v59, v139, v75
	v_fmac_f32_e32 v10, v155, v59
	v_fmac_f32_e32 v11, v181, v59
	v_fmac_f32_e32 v12, v197, v59
	v_fmac_f32_e32 v13, v213, v59
	v_mul_f32_e32 v59, v140, v76
	v_fmac_f32_e32 v10, v156, v59
	v_fmac_f32_e32 v11, v182, v59
	v_fmac_f32_e32 v12, v198, v59
	v_fmac_f32_e32 v13, v214, v59
	v_mul_f32_e32 v59, v141, v77
	v_fmac_f32_e32 v10, v157, v59
	v_fmac_f32_e32 v11, v183, v59
	v_fmac_f32_e32 v12, v199, v59
	v_fmac_f32_e32 v13, v215, v59
	v_mul_f32_e32 v59, v142, v78
	v_fmac_f32_e32 v10, v158, v59
	v_fmac_f32_e32 v11, v184, v59
	v_fmac_f32_e32 v12, v200, v59
	v_fmac_f32_e32 v13, v216, v59
	v_mul_f32_e32 v59, v143, v79
	v_fmac_f32_e32 v10, v159, v59
	v_fmac_f32_e32 v11, v185, v59
	v_fmac_f32_e32 v12, v201, v59
	v_fmac_f32_e32 v13, v217, v59
	ds_read_b128 v[128:131], v63 offset:2368
	ds_read_b128 v[132:135], v63 offset:2384
	ds_read_b128 v[136:139], v63 offset:2400
	ds_read_b128 v[140:143], v63 offset:2416
	ds_read_b128 v[144:147], v63 offset:320
	ds_read_b128 v[148:151], v63 offset:336
	ds_read_b128 v[152:155], v63 offset:352
	ds_read_b128 v[156:159], v63 offset:368
	ds_read_b128 v[170:173], v63 offset:832
	ds_read_b128 v[174:177], v63 offset:848
	ds_read_b128 v[178:181], v63 offset:864
	ds_read_b128 v[182:185], v63 offset:880
	ds_read_b128 v[186:189], v63 offset:1344
	ds_read_b128 v[190:193], v63 offset:1360
	ds_read_b128 v[194:197], v63 offset:1376
	ds_read_b128 v[198:201], v63 offset:1392
	ds_read_b128 v[202:205], v63 offset:1856
	ds_read_b128 v[206:209], v63 offset:1872
	ds_read_b128 v[210:213], v63 offset:1888
	ds_read_b128 v[214:217], v63 offset:1904
	s_waitcnt vmcnt(32)
	s_waitcnt lgkmcnt(0)
	v_mul_f32_e32 v59, v128, v80
	v_fmac_f32_e32 v10, v144, v59
	v_fmac_f32_e32 v11, v170, v59
	v_fmac_f32_e32 v12, v186, v59
	v_fmac_f32_e32 v13, v202, v59
	v_mul_f32_e32 v59, v129, v81
	v_fmac_f32_e32 v10, v145, v59
	v_fmac_f32_e32 v11, v171, v59
	v_fmac_f32_e32 v12, v187, v59
	v_fmac_f32_e32 v13, v203, v59
	v_mul_f32_e32 v59, v130, v82
	v_fmac_f32_e32 v10, v146, v59
	v_fmac_f32_e32 v11, v172, v59
	v_fmac_f32_e32 v12, v188, v59
	v_fmac_f32_e32 v13, v204, v59
	v_mul_f32_e32 v59, v131, v83
	v_fmac_f32_e32 v10, v147, v59
	v_fmac_f32_e32 v11, v173, v59
	v_fmac_f32_e32 v12, v189, v59
	v_fmac_f32_e32 v13, v205, v59
	v_mul_f32_e32 v59, v132, v84
	v_fmac_f32_e32 v10, v148, v59
	v_fmac_f32_e32 v11, v174, v59
	v_fmac_f32_e32 v12, v190, v59
	v_fmac_f32_e32 v13, v206, v59
	v_mul_f32_e32 v59, v133, v85
	v_fmac_f32_e32 v10, v149, v59
	v_fmac_f32_e32 v11, v175, v59
	v_fmac_f32_e32 v12, v191, v59
	v_fmac_f32_e32 v13, v207, v59
	v_mul_f32_e32 v59, v134, v86
	v_fmac_f32_e32 v10, v150, v59
	v_fmac_f32_e32 v11, v176, v59
	v_fmac_f32_e32 v12, v192, v59
	v_fmac_f32_e32 v13, v208, v59
	v_mul_f32_e32 v59, v135, v87
	v_fmac_f32_e32 v10, v151, v59
	v_fmac_f32_e32 v11, v177, v59
	v_fmac_f32_e32 v12, v193, v59
	v_fmac_f32_e32 v13, v209, v59
	v_mul_f32_e32 v59, v136, v88
	v_fmac_f32_e32 v10, v152, v59
	v_fmac_f32_e32 v11, v178, v59
	v_fmac_f32_e32 v12, v194, v59
	v_fmac_f32_e32 v13, v210, v59
	v_mul_f32_e32 v59, v137, v89
	v_fmac_f32_e32 v10, v153, v59
	v_fmac_f32_e32 v11, v179, v59
	v_fmac_f32_e32 v12, v195, v59
	v_fmac_f32_e32 v13, v211, v59
	v_mul_f32_e32 v59, v138, v90
	v_fmac_f32_e32 v10, v154, v59
	v_fmac_f32_e32 v11, v180, v59
	v_fmac_f32_e32 v12, v196, v59
	v_fmac_f32_e32 v13, v212, v59
	v_mul_f32_e32 v59, v139, v91
	v_fmac_f32_e32 v10, v155, v59
	v_fmac_f32_e32 v11, v181, v59
	v_fmac_f32_e32 v12, v197, v59
	v_fmac_f32_e32 v13, v213, v59
	v_mul_f32_e32 v59, v140, v92
	v_fmac_f32_e32 v10, v156, v59
	v_fmac_f32_e32 v11, v182, v59
	v_fmac_f32_e32 v12, v198, v59
	v_fmac_f32_e32 v13, v214, v59
	v_mul_f32_e32 v59, v141, v93
	v_fmac_f32_e32 v10, v157, v59
	v_fmac_f32_e32 v11, v183, v59
	v_fmac_f32_e32 v12, v199, v59
	v_fmac_f32_e32 v13, v215, v59
	v_mul_f32_e32 v59, v142, v94
	v_fmac_f32_e32 v10, v158, v59
	v_fmac_f32_e32 v11, v184, v59
	v_fmac_f32_e32 v12, v200, v59
	v_fmac_f32_e32 v13, v216, v59
	v_mul_f32_e32 v59, v143, v95
	v_fmac_f32_e32 v10, v159, v59
	v_fmac_f32_e32 v11, v185, v59
	v_fmac_f32_e32 v12, v201, v59
	v_fmac_f32_e32 v13, v217, v59
	ds_read_b128 v[128:131], v63 offset:2432
	ds_read_b128 v[132:135], v63 offset:2448
	ds_read_b128 v[136:139], v63 offset:2464
	ds_read_b128 v[140:143], v63 offset:2480
	ds_read_b128 v[144:147], v63 offset:384
	ds_read_b128 v[148:151], v63 offset:400
	ds_read_b128 v[152:155], v63 offset:416
	ds_read_b128 v[156:159], v63 offset:432
	ds_read_b128 v[170:173], v63 offset:896
	ds_read_b128 v[174:177], v63 offset:912
	ds_read_b128 v[178:181], v63 offset:928
	ds_read_b128 v[182:185], v63 offset:944
	ds_read_b128 v[186:189], v63 offset:1408
	ds_read_b128 v[190:193], v63 offset:1424
	ds_read_b128 v[194:197], v63 offset:1440
	ds_read_b128 v[198:201], v63 offset:1456
	ds_read_b128 v[202:205], v63 offset:1920
	ds_read_b128 v[206:209], v63 offset:1936
	ds_read_b128 v[210:213], v63 offset:1952
	ds_read_b128 v[214:217], v63 offset:1968
	s_waitcnt vmcnt(16)
	s_waitcnt lgkmcnt(0)
	v_mul_f32_e32 v59, v128, v96
	v_fmac_f32_e32 v10, v144, v59
	v_fmac_f32_e32 v11, v170, v59
	v_fmac_f32_e32 v12, v186, v59
	v_fmac_f32_e32 v13, v202, v59
	v_mul_f32_e32 v59, v129, v97
	v_fmac_f32_e32 v10, v145, v59
	v_fmac_f32_e32 v11, v171, v59
	v_fmac_f32_e32 v12, v187, v59
	v_fmac_f32_e32 v13, v203, v59
	v_mul_f32_e32 v59, v130, v98
	v_fmac_f32_e32 v10, v146, v59
	v_fmac_f32_e32 v11, v172, v59
	v_fmac_f32_e32 v12, v188, v59
	v_fmac_f32_e32 v13, v204, v59
	v_mul_f32_e32 v59, v131, v99
	v_fmac_f32_e32 v10, v147, v59
	v_fmac_f32_e32 v11, v173, v59
	v_fmac_f32_e32 v12, v189, v59
	v_fmac_f32_e32 v13, v205, v59
	v_mul_f32_e32 v59, v132, v100
	v_fmac_f32_e32 v10, v148, v59
	v_fmac_f32_e32 v11, v174, v59
	v_fmac_f32_e32 v12, v190, v59
	v_fmac_f32_e32 v13, v206, v59
	v_mul_f32_e32 v59, v133, v101
	v_fmac_f32_e32 v10, v149, v59
	v_fmac_f32_e32 v11, v175, v59
	v_fmac_f32_e32 v12, v191, v59
	v_fmac_f32_e32 v13, v207, v59
	v_mul_f32_e32 v59, v134, v102
	v_fmac_f32_e32 v10, v150, v59
	v_fmac_f32_e32 v11, v176, v59
	v_fmac_f32_e32 v12, v192, v59
	v_fmac_f32_e32 v13, v208, v59
	v_mul_f32_e32 v59, v135, v103
	v_fmac_f32_e32 v10, v151, v59
	v_fmac_f32_e32 v11, v177, v59
	v_fmac_f32_e32 v12, v193, v59
	v_fmac_f32_e32 v13, v209, v59
	v_mul_f32_e32 v59, v136, v104
	v_fmac_f32_e32 v10, v152, v59
	v_fmac_f32_e32 v11, v178, v59
	v_fmac_f32_e32 v12, v194, v59
	v_fmac_f32_e32 v13, v210, v59
	v_mul_f32_e32 v59, v137, v105
	v_fmac_f32_e32 v10, v153, v59
	v_fmac_f32_e32 v11, v179, v59
	v_fmac_f32_e32 v12, v195, v59
	v_fmac_f32_e32 v13, v211, v59
	v_mul_f32_e32 v59, v138, v106
	v_fmac_f32_e32 v10, v154, v59
	v_fmac_f32_e32 v11, v180, v59
	v_fmac_f32_e32 v12, v196, v59
	v_fmac_f32_e32 v13, v212, v59
	v_mul_f32_e32 v59, v139, v107
	v_fmac_f32_e32 v10, v155, v59
	v_fmac_f32_e32 v11, v181, v59
	v_fmac_f32_e32 v12, v197, v59
	v_fmac_f32_e32 v13, v213, v59
	v_mul_f32_e32 v59, v140, v108
	v_fmac_f32_e32 v10, v156, v59
	v_fmac_f32_e32 v11, v182, v59
	v_fmac_f32_e32 v12, v198, v59
	v_fmac_f32_e32 v13, v214, v59
	v_mul_f32_e32 v59, v141, v109
	v_fmac_f32_e32 v10, v157, v59
	v_fmac_f32_e32 v11, v183, v59
	v_fmac_f32_e32 v12, v199, v59
	v_fmac_f32_e32 v13, v215, v59
	v_mul_f32_e32 v59, v142, v110
	v_fmac_f32_e32 v10, v158, v59
	v_fmac_f32_e32 v11, v184, v59
	v_fmac_f32_e32 v12, v200, v59
	v_fmac_f32_e32 v13, v216, v59
	v_mul_f32_e32 v59, v143, v111
	v_fmac_f32_e32 v10, v159, v59
	v_fmac_f32_e32 v11, v185, v59
	v_fmac_f32_e32 v12, v201, v59
	v_fmac_f32_e32 v13, v217, v59
	ds_read_b128 v[128:131], v63 offset:2496
	ds_read_b128 v[132:135], v63 offset:2512
	ds_read_b128 v[136:139], v63 offset:2528
	ds_read_b128 v[140:143], v63 offset:2544
	ds_read_b128 v[144:147], v63 offset:448
	ds_read_b128 v[148:151], v63 offset:464
	ds_read_b128 v[152:155], v63 offset:480
	ds_read_b128 v[156:159], v63 offset:496
	ds_read_b128 v[170:173], v63 offset:960
	ds_read_b128 v[174:177], v63 offset:976
	ds_read_b128 v[178:181], v63 offset:992
	ds_read_b128 v[182:185], v63 offset:1008
	ds_read_b128 v[186:189], v63 offset:1472
	ds_read_b128 v[190:193], v63 offset:1488
	ds_read_b128 v[194:197], v63 offset:1504
	ds_read_b128 v[198:201], v63 offset:1520
	ds_read_b128 v[202:205], v63 offset:1984
	ds_read_b128 v[206:209], v63 offset:2000
	ds_read_b128 v[210:213], v63 offset:2016
	ds_read_b128 v[214:217], v63 offset:2032
	s_waitcnt vmcnt(0)
	s_waitcnt lgkmcnt(0)
	v_mul_f32_e32 v59, v128, v112
	v_fmac_f32_e32 v10, v144, v59
	v_fmac_f32_e32 v11, v170, v59
	v_fmac_f32_e32 v12, v186, v59
	v_fmac_f32_e32 v13, v202, v59
	v_mul_f32_e32 v59, v129, v113
	v_fmac_f32_e32 v10, v145, v59
	v_fmac_f32_e32 v11, v171, v59
	v_fmac_f32_e32 v12, v187, v59
	v_fmac_f32_e32 v13, v203, v59
	v_mul_f32_e32 v59, v130, v114
	v_fmac_f32_e32 v10, v146, v59
	v_fmac_f32_e32 v11, v172, v59
	v_fmac_f32_e32 v12, v188, v59
	v_fmac_f32_e32 v13, v204, v59
	v_mul_f32_e32 v59, v131, v115
	v_fmac_f32_e32 v10, v147, v59
	v_fmac_f32_e32 v11, v173, v59
	v_fmac_f32_e32 v12, v189, v59
	v_fmac_f32_e32 v13, v205, v59
	v_mul_f32_e32 v59, v132, v116
	v_fmac_f32_e32 v10, v148, v59
	v_fmac_f32_e32 v11, v174, v59
	v_fmac_f32_e32 v12, v190, v59
	v_fmac_f32_e32 v13, v206, v59
	v_mul_f32_e32 v59, v133, v117
	v_fmac_f32_e32 v10, v149, v59
	v_fmac_f32_e32 v11, v175, v59
	v_fmac_f32_e32 v12, v191, v59
	v_fmac_f32_e32 v13, v207, v59
	v_mul_f32_e32 v59, v134, v118
	v_fmac_f32_e32 v10, v150, v59
	v_fmac_f32_e32 v11, v176, v59
	v_fmac_f32_e32 v12, v192, v59
	v_fmac_f32_e32 v13, v208, v59
	v_mul_f32_e32 v59, v135, v119
	v_fmac_f32_e32 v10, v151, v59
	v_fmac_f32_e32 v11, v177, v59
	v_fmac_f32_e32 v12, v193, v59
	v_fmac_f32_e32 v13, v209, v59
	v_mul_f32_e32 v59, v136, v120
	v_fmac_f32_e32 v10, v152, v59
	v_fmac_f32_e32 v11, v178, v59
	v_fmac_f32_e32 v12, v194, v59
	v_fmac_f32_e32 v13, v210, v59
	v_mul_f32_e32 v59, v137, v121
	v_fmac_f32_e32 v10, v153, v59
	v_fmac_f32_e32 v11, v179, v59
	v_fmac_f32_e32 v12, v195, v59
	v_fmac_f32_e32 v13, v211, v59
	v_mul_f32_e32 v59, v138, v122
	v_fmac_f32_e32 v10, v154, v59
	v_fmac_f32_e32 v11, v180, v59
	v_fmac_f32_e32 v12, v196, v59
	v_fmac_f32_e32 v13, v212, v59
	v_mul_f32_e32 v59, v139, v123
	v_fmac_f32_e32 v10, v155, v59
	v_fmac_f32_e32 v11, v181, v59
	v_fmac_f32_e32 v12, v197, v59
	v_fmac_f32_e32 v13, v213, v59
	v_mul_f32_e32 v59, v140, v124
	v_fmac_f32_e32 v10, v156, v59
	v_fmac_f32_e32 v11, v182, v59
	v_fmac_f32_e32 v12, v198, v59
	v_fmac_f32_e32 v13, v214, v59
	v_mul_f32_e32 v59, v141, v125
	v_fmac_f32_e32 v10, v157, v59
	v_fmac_f32_e32 v11, v183, v59
	v_fmac_f32_e32 v12, v199, v59
	v_fmac_f32_e32 v13, v215, v59
	v_mul_f32_e32 v59, v142, v126
	v_fmac_f32_e32 v10, v158, v59
	v_fmac_f32_e32 v11, v184, v59
	v_fmac_f32_e32 v12, v200, v59
	v_fmac_f32_e32 v13, v216, v59
	v_mul_f32_e32 v59, v143, v127
	v_fmac_f32_e32 v10, v159, v59
	v_fmac_f32_e32 v11, v185, v59
	v_fmac_f32_e32 v12, v201, v59
	v_fmac_f32_e32 v13, v217, v59
	v_and_b32_e32 v2, 0x3ff, v0
	v_and_b32_e32 v4, -4, v58
	v_lshlrev_b32_e32 v2, 11, v2
	v_add_u32_e32 v0, s66, v0
	v_lshl_add_u64 v[8:9], s[64:65], 0, v[2:3]
	v_ashrrev_i32_e32 v5, 31, v4
	v_cmp_lt_i32_e32 vcc, s71, v0
	v_lshl_add_u64 v[4:5], v[4:5], 1, v[8:9]
	s_or_b64 s[18:19], vcc, s[18:19]
	v_subrev_u16_e32 v1, s66, v1
	v_cvt_pk_bf16_f32 v6, v10, v11
	v_cvt_pk_bf16_f32 v7, v12, v13
	global_store_dwordx2 v[4:5], v[6:7], off
	s_andn2_b64 exec, exec, s[18:19]
	s_cbranch_execnz .LBB0_67
